# adds XCD-aware tile order for phase-3 GEMM and double-buffered LDS operand reads in scan step 1
# baseline (speedup 1.0000x reference)
.LBB0_870:
	ds_read_b128 v[108:111], v181
	ds_read_b128 v[112:115], v180 offset:62464
	ds_read_b128 v[222:225], v181 offset:8704
	ds_read_b128 v[214:217], v181 offset:32
	ds_read_b128 v[116:119], v180 offset:62496
	ds_read_b128 v[218:221], v181 offset:8736
	ds_read_b128 v[226:229], v181 offset:64
	ds_read_b128 v[242:245], v180 offset:62528
	ds_read_b128 v[234:237], v181 offset:8768
	ds_read_b128 v[230:233], v181 offset:96
	ds_read_b128 v[246:249], v180 offset:62560
	ds_read_b128 v[238:241], v181 offset:8800
	s_waitcnt lgkmcnt(10)
	v_mfma_f32_32x32x16_bf16 v[32:47], v[108:111], v[112:115], v[32:47]
	s_waitcnt lgkmcnt(9)
	v_mfma_f32_32x32x16_bf16 v[48:63], v[222:225], v[112:115], v[48:63]
	s_waitcnt lgkmcnt(7)
	v_mfma_f32_32x32x16_bf16 v[32:47], v[214:217], v[116:119], v[32:47]
	s_waitcnt lgkmcnt(6)
	v_mfma_f32_32x32x16_bf16 v[48:63], v[218:221], v[116:119], v[48:63]
	ds_read_b128 v[108:111], v181 offset:128
	ds_read_b128 v[112:115], v180 offset:62592
	ds_read_b128 v[222:225], v181 offset:8832
	ds_read_b128 v[214:217], v181 offset:160
	ds_read_b128 v[116:119], v180 offset:62624
	ds_read_b128 v[218:221], v181 offset:8864
	s_waitcnt lgkmcnt(10)
	v_mfma_f32_32x32x16_bf16 v[32:47], v[226:229], v[242:245], v[32:47]
	s_waitcnt lgkmcnt(9)
	v_mfma_f32_32x32x16_bf16 v[48:63], v[234:237], v[242:245], v[48:63]
	s_waitcnt lgkmcnt(7)
	v_mfma_f32_32x32x16_bf16 v[32:47], v[230:233], v[246:249], v[32:47]
	s_waitcnt lgkmcnt(6)
	v_mfma_f32_32x32x16_bf16 v[48:63], v[238:241], v[246:249], v[48:63]
	ds_read_b128 v[226:229], v181 offset:192
	ds_read_b128 v[242:245], v180 offset:62656
	ds_read_b128 v[234:237], v181 offset:8896
	ds_read_b128 v[230:233], v181 offset:224
	ds_read_b128 v[246:249], v180 offset:62688
	ds_read_b128 v[238:241], v181 offset:8928
	s_waitcnt lgkmcnt(10)
	v_mfma_f32_32x32x16_bf16 v[32:47], v[108:111], v[112:115], v[32:47]
	s_waitcnt lgkmcnt(9)
	v_mfma_f32_32x32x16_bf16 v[48:63], v[222:225], v[112:115], v[48:63]
	s_waitcnt lgkmcnt(7)
	v_mfma_f32_32x32x16_bf16 v[32:47], v[214:217], v[116:119], v[32:47]
	s_waitcnt lgkmcnt(6)
	v_mfma_f32_32x32x16_bf16 v[48:63], v[218:221], v[116:119], v[48:63]
	v_lshl_add_u64 v[112:113], v[168:169], 0, v[164:165]
	global_load_dwordx4 v[108:111], v[112:113], off
	s_nop 0
	global_load_dwordx4 v[112:115], v[112:113], off offset:-16
	s_waitcnt lgkmcnt(4)
	v_mfma_f32_32x32x16_bf16 v[32:47], v[226:229], v[242:245], v[32:47]
	s_waitcnt lgkmcnt(3)
	v_mfma_f32_32x32x16_bf16 v[48:63], v[234:237], v[242:245], v[48:63]
	s_waitcnt lgkmcnt(1)
	v_mfma_f32_32x32x16_bf16 v[32:47], v[230:233], v[246:249], v[32:47]
	s_waitcnt lgkmcnt(0)
	v_mfma_f32_32x32x16_bf16 v[48:63], v[238:241], v[246:249], v[48:63]
	s_and_saveexec_b64 s[52:53], s[10:11]
	s_cbranch_execz .LBB0_872
	s_nop 7
	v_cvt_pk_bf16_f32 v116, v32, v33
	v_cvt_pk_bf16_f32 v117, v34, v35
	v_cvt_pk_bf16_f32 v122, v36, v37
	v_cvt_pk_bf16_f32 v123, v38, v39
	v_cvt_pk_bf16_f32 v118, v48, v49
	v_cvt_pk_bf16_f32 v119, v50, v51
	v_cvt_pk_bf16_f32 v208, v52, v53
	v_cvt_pk_bf16_f32 v209, v54, v55
	ds_write2_b64 v182, v[116:117], v[122:123] offset1:2
	ds_write2_b64 v182, v[118:119], v[208:209] offset0:8 offset1:10
	v_cvt_pk_bf16_f32 v116, v40, v41
	v_cvt_pk_bf16_f32 v117, v42, v43
	v_cvt_pk_bf16_f32 v122, v44, v45
	v_cvt_pk_bf16_f32 v123, v46, v47
	v_cvt_pk_bf16_f32 v118, v56, v57
	v_cvt_pk_bf16_f32 v119, v58, v59
	v_cvt_pk_bf16_f32 v208, v60, v61
	v_cvt_pk_bf16_f32 v209, v62, v63
	ds_write2_b64 v182, v[116:117], v[122:123] offset0:4 offset1:6
	ds_write2_b64 v182, v[118:119], v[208:209] offset0:12 offset1:14

	.amdhsa_kernel _Z4mega6Paramsii
		.amdhsa_group_segment_fixed_size 0
		.amdhsa_private_segment_fixed_size 0
		.amdhsa_kernarg_size 544
		.amdhsa_user_sgpr_count 2
		.amdhsa_user_sgpr_dispatch_ptr 0
		.amdhsa_user_sgpr_queue_ptr 0
		.amdhsa_user_sgpr_kernarg_segment_ptr 1
		.amdhsa_user_sgpr_dispatch_id 0
		.amdhsa_user_sgpr_kernarg_preload_length 0
		.amdhsa_user_sgpr_kernarg_preload_offset 0
		.amdhsa_user_sgpr_private_segment_size 0
		.amdhsa_uses_dynamic_stack 0
		.amdhsa_enable_private_segment 0
		.amdhsa_system_sgpr_workgroup_id_x 1
		.amdhsa_system_sgpr_workgroup_id_y 0
		.amdhsa_system_sgpr_workgroup_id_z 0
		.amdhsa_system_sgpr_workgroup_info 0
		.amdhsa_system_vgpr_workitem_id 2
		.amdhsa_next_free_vgpr 256
		.amdhsa_next_free_sgpr 102
		.amdhsa_accum_offset 256
		.amdhsa_reserve_vcc 1
		.amdhsa_float_round_mode_32 0
		.amdhsa_float_round_mode_16_64 0
		.amdhsa_float_denorm_mode_32 3
		.amdhsa_float_denorm_mode_16_64 3
		.amdhsa_dx10_clamp 1
		.amdhsa_ieee_mode 1
		.amdhsa_fp16_overflow 0
		.amdhsa_tg_split 0
		.amdhsa_exception_fp_ieee_invalid_op 0
		.amdhsa_exception_fp_denorm_src 0
		.amdhsa_exception_fp_ieee_div_zero 0
		.amdhsa_exception_fp_ieee_overflow 0
		.amdhsa_exception_fp_ieee_underflow 0
		.amdhsa_exception_fp_ieee_inexact 0
		.amdhsa_exception_int_div_zero 0
	.end_amdhsa_kernel

amdhsa.kernels:
  - .agpr_count:     0
    .args:
      - .offset:         0
        .size:           280
        .value_kind:     by_value
      - .offset:         280
        .size:           4
        .value_kind:     by_value
      - .offset:         284
        .size:           4
        .value_kind:     by_value
      - .offset:         288
        .size:           4
        .value_kind:     hidden_block_count_x
      - .offset:         292
        .size:           4
        .value_kind:     hidden_block_count_y
      - .offset:         296
        .size:           4
        .value_kind:     hidden_block_count_z
      - .offset:         300
        .size:           2
        .value_kind:     hidden_group_size_x
      - .offset:         302
        .size:           2
        .value_kind:     hidden_group_size_y
      - .offset:         304
        .size:           2
        .value_kind:     hidden_group_size_z
      - .offset:         306
        .size:           2
        .value_kind:     hidden_remainder_x
      - .offset:         308
        .size:           2
        .value_kind:     hidden_remainder_y
      - .offset:         310
        .size:           2
        .value_kind:     hidden_remainder_z
      - .offset:         328
        .size:           8
        .value_kind:     hidden_global_offset_x
      - .offset:         336
        .size:           8
        .value_kind:     hidden_global_offset_y
      - .offset:         344
        .size:           8
        .value_kind:     hidden_global_offset_z
      - .offset:         352
        .size:           2
        .value_kind:     hidden_grid_dims
      - .offset:         376
        .size:           8
        .value_kind:     hidden_multigrid_sync_arg
      - .offset:         408
        .size:           4
        .value_kind:     hidden_dynamic_lds_size
    .group_segment_fixed_size: 0
    .kernarg_segment_align: 8
    .kernarg_segment_size: 544
    .language:       OpenCL C
    .language_version:
      - 2
      - 0
    .max_flat_workgroup_size: 512
    .name:           _Z4mega6Paramsii
    .private_segment_fixed_size: 0
    .sgpr_count:     104
    .sgpr_spill_count: 8
    .symbol:         _Z4mega6Paramsii.kd
    .uniform_work_group_size: 1
    .uses_dynamic_stack: false
    .vgpr_count:     256
    .vgpr_spill_count: 0
    .wavefront_size: 64
